# exp_ssmdbl
# baseline (speedup 1.0000x reference)
; __device__ __forceinline__ void ssm_item(const Params& p, int layer, int item, const int tidx) {
;   const int bg = item & 127;
;   const int b = bg >> 6, g = bg & 63, lg = layer * 64 + g;
;   const int tid = tidx, wid = tid >> 6, lane = tid & 63, n = lane & 31, half = lane >> 5;
;   constexpr int USTR = 2064, XSTR = 272;
;   char* U = smem;
;   float* S = (float*)(smem + 32 * USTR);
;   char* XIN = smem + 32 * USTR + 32768;
;   const u16* proj_u = (const u16*)(p.ws + WS_PROJ) + (size_t)b * SEQ * DIN + OFF_SU + g * 16;
;   const u16* KM = (const u16*)(p.ws + WS_KM) + (size_t)lg * 64 * 256;
;   const u16* E = (const u16*)(p.ws + WS_E) + (size_t)lg * 128 * 1024;
;   const u16* F = (const u16*)(p.ws + WS_F) + (size_t)lg * 1024 * 128;
;   const float* LAML = (const float*)(p.ws + WS_LAML) + (size_t)lg * 128;
;   u16* hs = (u16*)(p.ws + WS_HS);
;   float xre = 0.f, xim = 0.f, lre = 0.f, lim = 0.f;
;   if (tid < 64) { lre = LAML[tid * 2]; lim = LAML[tid * 2 + 1]; }
;   f32x4 dsk[2];
;   dsk[0] = *reinterpret_cast<const f32x4*>(p.d_skip + layer * 1024 + g * 16 + 4 * half);
;   dsk[1] = *reinterpret_cast<const f32x4*>(p.d_skip + layer * 1024 + g * 16 + 8 + 4 * half);
.LBB0_197:
	s_andn2_b64 vcc, exec, s[6:7]
	s_cbranch_vccnz .LBB0_71
	s_mov_b32 s99, 0
.Lsd_again_j:
	v_cmp_gt_i32_e64 s[6:7], 64, v164
	v_cmp_lt_i32_e32 vcc, 63, v164
	v_lshlrev_b32_e32 v92, 1, v164
	s_and_saveexec_b64 s[8:9], vcc
	s_xor_b64 s[8:9], exec, s[8:9]
	v_lshlrev_b32_e32 v92, 1, v164
	s_or_saveexec_b64 s[10:11], s[8:9]
	s_and_b32 s12, s64, 63
	s_or_b32 s8, s12, s68
	s_ashr_i32 s9, s8, 31
	v_mov_b32_e32 v94, 0
	v_mov_b32_e32 v95, 0
	s_xor_b64 exec, exec, s[10:11]
	s_cbranch_execz .LBB0_202
	s_lshl_b64 s[14:15], s[8:9], 9
	v_readlane_b32 s13, v255, 33
	s_add_u32 s14, s13, s14
	v_readlane_b32 s13, v255, 34
	s_addc_u32 s15, s13, s15
	v_ashrrev_i32_e32 v93, 31, v92
	v_lshl_add_u64 v[0:1], v[92:93], 2, s[14:15]
	global_load_dwordx2 v[94:95], v[0:1], off

; __device__ __forceinline__ void phase_mixers(const Params& p, int cidx, int layer) {
;     ...
;   for (;;) {
;     const int tidx = opaque_tid();
;     const int wid = tidx >> 6;
;     __syncthreads();
;     if (tidx == 0) s_item = atomicAdd(ctr, 1);
;     __syncthreads();
;     const int it = s_item;
;     if (it >= N_SSM + N_POOL + N_ATT + n_cv) break;
;     if (it < N_SSM) ssm_item(p, layer, it & 127, tidx);
;     else if (it < N_SSM + N_POOL) pool_block_item(p, layer, (it - N_SSM) & 255, tidx);
;     else if (it < N_SSM + N_POOL + N_ATT) attn_wave_item(p, ((it - N_SSM - N_POOL) & 511) * 8 + wid, tidx);
;     else cv_item_B(p, (it - N_SSM - N_POOL - N_ATT) % CV_B, tidx);
.Lsd_exit:
	s_cmp_eq_u32 s99, 0
	s_cbranch_scc0 .LBB0_71
	s_mov_b32 s99, 1
	v_mov_b32_e32 v164, v210
	s_barrier
	s_branch .Lsd_again_j
